# P3 small-M path re-tiled (256 workgroups x 16 rows x 32 cols, both branch GEMMs), on top of v31
# baseline (speedup 1.0000x reference)
; #define LAS __attribute__((address_space(3)))
; __device__ __forceinline__ SmallId small_id() { int tid = threadIdx.x; asm volatile("" : "+v"(tid)); SmallId i; i.w = __builtin_amdgcn_readfirstlane(tid >> 6); i.fr = tid & 15; i.fq = (tid & 63) >> 4; i.row = MP + 16 * i.w + i.fr; return i; }
; __device__ __forceinline__ void small_mix(const Params& p, int l, LAS unsigned char* lds, int G, int bx) {
;     const SmallId id = small_id();
;     const bf16_t* AD = (const bf16_t*)(p.ws + WS_AD); const bf16_t* Bm = (const bf16_t*)(p.ws + WS_W + (size_t)l * W_LAYER + WO_MIX); const bf16_t* PROJ = (const bf16_t*)(p.ws + WS_PROJ); bf16_t* MIX = (bf16_t*)(p.ws + WS_MIX);
;     for (int ts = G - 1 - bx; ts < DM / 32; ts += G) {
;         const int n0 = ts * 32; f32x4 ya[2] = {(f32x4){0.f, 0.f, 0.f, 0.f}, (f32x4){0.f, 0.f, 0.f, 0.f}}, yb[2] = {(f32x4){0.f, 0.f, 0.f, 0.f}, (f32x4){0.f, 0.f, 0.f, 0.f}};
;         small_mma_ksplit<2>(ya, AD, DM, Bm, 512, n0, lds, id);
;         small_mma_ksplit<2>(yb, AD + 512, DM, Bm + (size_t)1024 * 512, 512, n0, lds, id);
.LBB0_707:
	s_or_b64 exec, exec, s[0:1]
	v_readlane_b32 s2, v247, 8
	s_add_u32 s54, s86, 0xba00000
	s_waitcnt lgkmcnt(0)
	v_mov_b32_e32 v0, v222
	v_readlane_b32 s3, v247, 9
	v_readlane_b32 s52, v246, 20
	s_addc_u32 s55, s87, 0
	s_barrier
	s_and_b64 vcc, exec, s[2:3]
	v_readfirstlane_b32 s0, v0
	v_readlane_b32 s53, v246, 21
	s_mul_i32 s1, s93, 0x1b00000
	s_add_u32 s2, s86, s1
	s_addc_u32 s3, s87, 0
	s_ashr_i32 s7, s0, 6
	s_lshl_b32 s1, s7, 4
	v_and_b32_e32 v148, 15, v0
	s_add_i32 s1, s1, 0x8000
	s_andn2_b32 s0, s0, 63
	v_or_b32_e32 v2, s1, v148
	s_ashr_i32 s1, s0, 31
	v_lshl_or_b32 v96, v148, 11, v228
	s_lshl_b64 s[0:1], s[0:1], 1
	v_bfe_u32 v3, v0, 4, 2
	v_lshl_add_u64 v[4:5], s[48:49], 0, v[96:97]
	s_add_u32 s2, s2, s0
	v_lshl_add_u64 v[4:5], v[4:5], 0, s[0:1]
	v_lshlrev_b32_e32 v6, 4, v3
	v_mov_b32_e32 v7, v97
	s_addc_u32 s3, s3, s1
	v_lshl_add_u64 v[130:131], v[4:5], 0, v[6:7]
	v_lshl_add_u64 v[4:5], s[2:3], 0, v[6:7]
	s_mov_b64 s[2:3], 0x780000
	v_lshl_add_u64 v[132:133], v[4:5], 0, s[2:3]
	s_lshl_b32 s2, s7, 14
	v_lshlrev_b32_e32 v0, 4, v0
	s_add_i32 s2, s2, 0
	v_and_b32_e32 v0, 0x3f0, v0
	v_add_u32_e32 v149, s2, v0
	s_lshl_b32 s2, s7, 11
	s_add_i32 s2, s2, 0
	s_add_i32 s3, s2, 0x10400
	v_add_u32_e32 v152, s3, v0
	s_add_i32 s3, s2, 0x14400
	v_add_u32_e32 v150, s2, v0
	v_add_u32_e32 v154, s3, v0
	s_add_i32 s3, s2, 0x18400
	s_add_i32 s2, s2, 0x1c400
	v_add_u32_e32 v156, s3, v0
	v_add_u32_e32 v158, s2, v0
	v_lshl_add_u64 v[0:1], s[86:87], 0, v[96:97]
	v_lshl_add_u64 v[0:1], v[0:1], 0, s[0:1]
	v_lshl_add_u64 v[0:1], v[0:1], 0, v[6:7]
	s_mov_b64 s[0:1], 0x7900400
	v_lshl_add_u64 v[134:135], v[0:1], 0, s[0:1]
	s_mov_b64 s[0:1], 0x880000
	v_mov_b64_e32 v[0:1], s[84:85]
	v_lshl_add_u64 v[136:137], v[4:5], 0, s[0:1]
	v_lshlrev_b32_e32 v96, 2, v3
	v_ashrrev_i32_e32 v3, 31, v2
	v_mad_i64_i32 v[138:139], s[0:1], v2, s89, v[0:1]
	s_mov_b64 s[0:1], 0x1200
	v_lshlrev_b64 v[0:1], 11, v[2:3]
	v_add_u32_e32 v151, 0x10000, v150
	v_add_u32_e32 v153, 0x14000, v150
	v_add_u32_e32 v155, 0x18000, v150
	v_add_u32_e32 v157, 0x1c000, v150
	v_lshl_add_u64 v[140:141], v[138:139], 0, s[0:1]
	v_lshl_add_u64 v[142:143], s[54:55], 0, v[0:1]
	v_readlane_b32 s7, v246, 8
	s_lshr_b32 s32, s7, 6
	s_and_b32 s7, s7, 7
	s_lshl_b32 s7, s7, 2
	s_add_i32 s7, s7, s32

; #define LAS __attribute__((address_space(3)))
; template <int KSTEPS  >
; __device__ __forceinline__ void small_mma_ksplit(f32x4 (&acc)[2], const bf16_t* A, int lda, const bf16_t* Bt, int ldb, int n0, LAS unsigned char* lds, const SmallId& id) {
;     const int lane = id.fq * 16 + id.fr, k0 = id.w * (KSTEPS * 32);
;     f32x4 part[8][2];
; #pragma unroll
;     for (int rb = 0; rb < 8; ++rb) { part[rb][0] = (f32x4){0.f, 0.f, 0.f, 0.f}; part[rb][1] = part[rb][0]; }
;     const bf16_t* ap = A + (size_t)(MP + id.fr) * lda + k0 + 8 * id.fq;
;     const bf16_t* bp = Bt + (size_t)(n0 + id.fr) * ldb + k0 + 8 * id.fq;
; #pragma unroll 1
;     for (int ks = 0; ks < KSTEPS; ++ks) {
;         bf16x8 a[8], b[2];
; #pragma unroll
;         for (int rb = 0; rb < 8; ++rb) a[rb] = *(const bf16x8*)(ap + (size_t)(16 * rb) * lda + 32 * ks);
;         b[0] = *(const bf16x8*)(bp + 32 * ks); b[1] = *(const bf16x8*)(bp + (size_t)16 * ldb + 32 * ks);
; #pragma unroll
;         for (int rb = 0; rb < 8; ++rb) { part[rb][0] = __builtin_amdgcn_mfma_f32_16x16x32_bf16(b[0], a[rb], part[rb][0], 0, 0, 0); part[rb][1] = __builtin_amdgcn_mfma_f32_16x16x32_bf16(b[1], a[rb], part[rb][1], 0, 0, 0); }
;     }
;     LAS f32x4* red = (LAS f32x4*)lds;
; #pragma unroll
;     for (int rb = 0; rb < 8; ++rb) { red[((id.w * 8 + rb) * 2 + 0) * 64 + lane] = part[rb][0]; red[((id.w * 8 + rb) * 2 + 1) * 64 + lane] = part[rb][1]; }
;     asm volatile("s_waitcnt lgkmcnt(0)" ::: "memory"); __syncthreads();
;     acc[0] = (f32x4){0.f, 0.f, 0.f, 0.f}; acc[1] = acc[0];
; #pragma unroll
;     for (int w2 = 0; w2 < 8; ++w2) { acc[0] += red[((w2 * 8 + id.w) * 2 + 0) * 64 + lane]; acc[1] += red[((w2 * 8 + id.w) * 2 + 1) * 64 + lane]; }
;     asm volatile("s_waitcnt lgkmcnt(0)" ::: "memory"); __syncthreads();
; __device__ __forceinline__ void small_mix(const Params& p, int l, LAS unsigned char* lds, int G, int bx) {
;     ...
;         small_mma_ksplit<2>(ya, AD, DM, Bm, 512, n0, lds, id);
;         small_mma_ksplit<2>(yb, AD + 512, DM, Bm + (size_t)1024 * 512, 512, n0, lds, id);
.LBB0_710:
	s_waitcnt lgkmcnt(0)
	v_readlane_b32 s2, v246, 8
	v_readfirstlane_b32 s32, v222
	s_bfe_u32 s2, s2, 0x30003
	s_lshr_b32 s32, s32, 6
	s_cmp_eq_u32 s32, s2
	s_cselect_b32 s32, 1, 0
	s_lshl_b32 s3, s2, 11
	v_add_u32_e32 v68, s3, v149
	s_mul_i32 s2, s2, s9
	s_mov_b32 s3, 0
	v_lshl_add_u64 v[70:71], v[130:131], 0, s[2:3]
	global_load_dwordx4 v[76:79], v[70:71], off
	global_load_dwordx4 v[80:83], v[64:65], off
	global_load_dwordx4 v[84:87], v[66:67], off
	global_load_dwordx4 v[88:91], v[70:71], off offset:64
	global_load_dwordx4 v[92:95], v[64:65], off offset:64
	global_load_dwordx4 v[98:101], v[66:67], off offset:64
	s_waitcnt vmcnt(3)
	v_mfma_f32_16x16x32_bf16 v[36:39], v[80:83], v[76:79], v[36:39]
	v_mfma_f32_16x16x32_bf16 v[24:27], v[84:87], v[76:79], v[24:27]
	s_waitcnt vmcnt(0)
	v_mfma_f32_16x16x32_bf16 v[36:39], v[92:95], v[88:91], v[36:39]
	v_mfma_f32_16x16x32_bf16 v[24:27], v[98:101], v[88:91], v[24:27]
	s_nop 7
	s_nop 1
	ds_write_b128 v68, v[36:39]
	ds_write_b128 v68, v[24:27] offset:1024
	s_waitcnt lgkmcnt(0)
	s_waitcnt lgkmcnt(0)
	s_barrier
	ds_read_b128 v[126:129], v150
	ds_read_b128 v[122:125], v150 offset:1024
	ds_read_b128 v[118:121], v150 offset:16384
	ds_read_b128 v[114:117], v150 offset:17408
	ds_read_b128 v[110:113], v150 offset:32768
	ds_read_b128 v[106:109], v150 offset:33792
	ds_read_b128 v[102:105], v150 offset:49152
	ds_read_b128 v[98:101], v150 offset:50176
	ds_read_b128 v[92:95], v151
	ds_read_b128 v[88:91], v152
	ds_read_b128 v[84:87], v153
	ds_read_b128 v[80:83], v154
	ds_read_b128 v[76:79], v155
	ds_read_b128 v[72:75], v156
	ds_read_b128 v[68:71], v157
	ds_read_b128 v[64:67], v158
	s_waitcnt lgkmcnt(0)
	v_lshl_add_u64 v[144:145], v[136:137], 0, v[144:145]
	s_mov_b64 s[0:1], 0x4000
	v_mov_b32_e32 v0, 0
	v_lshl_add_u64 v[146:147], v[144:145], 0, s[0:1]
	s_mov_b64 s[2:3], 0
	s_mov_b64 s[0:1], -1
	v_mov_b32_e32 v1, v0
	v_mov_b32_e32 v2, v0
	v_mov_b32_e32 v3, v0
	v_mov_b32_e32 v4, v0
	v_mov_b32_e32 v5, v0
	v_mov_b32_e32 v6, v0
	v_mov_b32_e32 v7, v0
	v_mov_b32_e32 v8, v0
	v_mov_b32_e32 v9, v0
	v_mov_b32_e32 v10, v0
	v_mov_b32_e32 v11, v0
	v_mov_b32_e32 v12, v0
	v_mov_b32_e32 v13, v0
	v_mov_b32_e32 v14, v0
	v_mov_b32_e32 v15, v0
	v_mov_b32_e32 v16, v0
	v_mov_b32_e32 v17, v0
	v_mov_b32_e32 v18, v0
	v_mov_b32_e32 v19, v0
	v_mov_b32_e32 v20, v0
	v_mov_b32_e32 v21, v0
	v_mov_b32_e32 v22, v0
	v_mov_b32_e32 v23, v0
	v_mov_b32_e32 v24, v0
	v_mov_b32_e32 v25, v0
	v_mov_b32_e32 v26, v0
	v_mov_b32_e32 v27, v0
	v_mov_b32_e32 v36, v0
	v_mov_b32_e32 v37, v0
	v_mov_b32_e32 v38, v0
	v_mov_b32_e32 v39, v0
	v_mov_b32_e32 v28, v0
	v_mov_b32_e32 v29, v0
	v_mov_b32_e32 v30, v0
	v_mov_b32_e32 v31, v0
	v_mov_b32_e32 v32, v0
	v_mov_b32_e32 v33, v0
	v_mov_b32_e32 v34, v0
	v_mov_b32_e32 v35, v0
	v_mov_b32_e32 v40, v0
	v_mov_b32_e32 v41, v0
	v_mov_b32_e32 v42, v0
	v_mov_b32_e32 v43, v0
	v_mov_b32_e32 v44, v0
	v_mov_b32_e32 v45, v0
	v_mov_b32_e32 v46, v0
	v_mov_b32_e32 v47, v0
	v_mov_b32_e32 v48, v0
	v_mov_b32_e32 v49, v0
	v_mov_b32_e32 v50, v0
	v_mov_b32_e32 v51, v0
	v_mov_b32_e32 v52, v0
	v_mov_b32_e32 v53, v0
	v_mov_b32_e32 v54, v0
	v_mov_b32_e32 v55, v0
	v_mov_b32_e32 v56, v0
	v_mov_b32_e32 v57, v0
	v_mov_b32_e32 v58, v0
	v_mov_b32_e32 v59, v0
	v_mov_b32_e32 v60, v0
	v_mov_b32_e32 v61, v0
	v_mov_b32_e32 v62, v0
	v_mov_b32_e32 v63, v0
	s_waitcnt lgkmcnt(0)
	s_barrier
.LBB0_712:
	s_waitcnt lgkmcnt(0)
	v_readlane_b32 s2, v246, 8
	v_readfirstlane_b32 s32, v222
	s_bfe_u32 s2, s2, 0x30003
	s_lshr_b32 s32, s32, 6
	s_cmp_eq_u32 s32, s2
	s_cselect_b32 s32, 1, 0
	s_lshl_b32 s3, s2, 11
	v_add_u32_e32 v130, s3, v149
	s_mul_i32 s2, s2, s9
	s_mov_b32 s3, 0
	v_lshl_add_u64 v[132:133], v[134:135], 0, s[2:3]
	global_load_dwordx4 v[162:165], v[132:133], off
	global_load_dwordx4 v[166:169], v[144:145], off
	global_load_dwordx4 v[170:173], v[146:147], off
	global_load_dwordx4 v[174:177], v[132:133], off offset:64
	global_load_dwordx4 v[178:181], v[144:145], off offset:64
	global_load_dwordx4 v[182:185], v[146:147], off offset:64
	s_waitcnt vmcnt(3)
	v_mfma_f32_16x16x32_bf16 v[36:39], v[166:169], v[162:165], v[36:39]
	v_mfma_f32_16x16x32_bf16 v[24:27], v[170:173], v[162:165], v[24:27]
	s_waitcnt vmcnt(0)
	v_mfma_f32_16x16x32_bf16 v[36:39], v[178:181], v[174:177], v[36:39]
	v_mfma_f32_16x16x32_bf16 v[24:27], v[182:185], v[174:177], v[24:27]
	s_nop 7
	s_nop 1
	ds_write_b128 v130, v[36:39]
	ds_write_b128 v130, v[24:27] offset:1024
	s_waitcnt lgkmcnt(0)
	s_waitcnt lgkmcnt(0)
	s_barrier
; __device__ __forceinline__ unsigned cvt_pk_bf16(float lo, float hi) { unsigned r; asm volatile("v_cvt_pk_bf16_f32 %0, %1, %2" : "=v"(r) : "v"(lo), "v"(hi)); return r; }
; template <int KSTEPS  >
; __device__ __forceinline__ void small_mma_ksplit(f32x4 (&acc)[2], const bf16_t* A, int lda, const bf16_t* Bt, int ldb, int n0, LAS unsigned char* lds, const SmallId& id) {
;     ...
;     acc[0] = (f32x4){0.f, 0.f, 0.f, 0.f}; acc[1] = acc[0];
; #pragma unroll
;     for (int w2 = 0; w2 < 8; ++w2) { acc[0] += red[((w2 * 8 + id.w) * 2 + 0) * 64 + lane]; acc[1] += red[((w2 * 8 + id.w) * 2 + 1) * 64 + lane]; }
;     asm volatile("s_waitcnt lgkmcnt(0)" ::: "memory"); __syncthreads();
; __device__ __forceinline__ void small_mix(const Params& p, int l, LAS unsigned char* lds, int G, int bx) {
;     ...
; #pragma unroll
;         for (int nb = 0; nb < 2; ++nb) { const int col = n0 + 16 * nb + 4 * id.fq;
;             const u32x2 g0 = *(const u32x2*)(PROJ + (size_t)id.row * INW + 1280 + col), g1 = *(const u32x2*)(PROJ + (size_t)id.row * INW + 2304 + col);
;             const float v0 = bf_lo(g0.x) * ya[nb][0] + bf_lo(g1.x) * yb[nb][0], v1 = bf_hi(g0.x) * ya[nb][1] + bf_hi(g1.x) * yb[nb][1];
;             const float v2 = bf_lo(g0.y) * ya[nb][2] + bf_lo(g1.y) * yb[nb][2], v3 = bf_hi(g0.y) * ya[nb][3] + bf_hi(g1.y) * yb[nb][3];
;             u32x2 w; w.x = cvt_pk_bf16(v0, v1); w.y = cvt_pk_bf16(v2, v3); *(u32x2*)(MIX + (size_t)id.row * DM + col) = w; }
	ds_read_b128 v[0:3], v150
	v_pk_add_f32 v[126:127], v[126:127], 0 op_sel_hi:[1,0]
	v_pk_add_f32 v[128:129], v[128:129], 0 op_sel_hi:[1,0]
	v_pk_add_f32 v[118:119], v[126:127], v[118:119]
	v_pk_add_f32 v[120:121], v[128:129], v[120:121]
	s_waitcnt lgkmcnt(0)
	v_pk_add_f32 v[4:5], v[2:3], 0 op_sel_hi:[1,0]
	v_pk_add_f32 v[6:7], v[0:1], 0 op_sel_hi:[1,0]
	ds_read_b128 v[0:3], v150 offset:1024
	v_pk_add_f32 v[110:111], v[118:119], v[110:111]
	v_pk_add_f32 v[112:113], v[120:121], v[112:113]
	v_pk_add_f32 v[102:103], v[110:111], v[102:103]
	v_pk_add_f32 v[104:105], v[112:113], v[104:105]
	s_waitcnt lgkmcnt(0)
	v_pk_add_f32 v[8:9], v[2:3], 0 op_sel_hi:[1,0]
	v_pk_add_f32 v[10:11], v[0:1], 0 op_sel_hi:[1,0]
	ds_read_b128 v[0:3], v150 offset:16384
	v_pk_add_f32 v[92:93], v[102:103], v[92:93]
	v_pk_add_f32 v[94:95], v[104:105], v[94:95]
	v_pk_add_f32 v[84:85], v[92:93], v[84:85]
	v_pk_add_f32 v[86:87], v[94:95], v[86:87]
	s_waitcnt lgkmcnt(0)
	v_pk_add_f32 v[4:5], v[4:5], v[2:3]
	v_pk_add_f32 v[6:7], v[6:7], v[0:1]
	ds_read_b128 v[0:3], v150 offset:17408
	v_pk_add_f32 v[76:77], v[84:85], v[76:77]
	v_pk_add_f32 v[78:79], v[86:87], v[78:79]
	v_pk_add_f32 v[68:69], v[76:77], v[68:69]
	v_pk_add_f32 v[70:71], v[78:79], v[70:71]
	s_waitcnt lgkmcnt(0)
	v_pk_add_f32 v[8:9], v[8:9], v[2:3]
	v_pk_add_f32 v[10:11], v[10:11], v[0:1]
	ds_read_b128 v[0:3], v150 offset:32768
	v_mov_b32_e32 v20, v68
	v_pk_add_f32 v[122:123], v[122:123], 0 op_sel_hi:[1,0]
	v_pk_add_f32 v[124:125], v[124:125], 0 op_sel_hi:[1,0]
	v_pk_add_f32 v[114:115], v[122:123], v[114:115]
	s_waitcnt lgkmcnt(0)
	v_pk_add_f32 v[4:5], v[4:5], v[2:3]
	v_pk_add_f32 v[6:7], v[6:7], v[0:1]
	ds_read_b128 v[0:3], v150 offset:33792
	v_pk_add_f32 v[106:107], v[114:115], v[106:107]
	v_pk_add_f32 v[116:117], v[124:125], v[116:117]
	v_pk_add_f32 v[98:99], v[106:107], v[98:99]
	v_pk_add_f32 v[108:109], v[116:117], v[108:109]
	s_waitcnt lgkmcnt(0)
	v_pk_add_f32 v[8:9], v[8:9], v[2:3]
	v_pk_add_f32 v[10:11], v[10:11], v[0:1]
	ds_read_b128 v[0:3], v150 offset:49152
	v_pk_add_f32 v[88:89], v[98:99], v[88:89]
	v_pk_add_f32 v[100:101], v[108:109], v[100:101]
	v_pk_add_f32 v[80:81], v[88:89], v[80:81]
	v_pk_add_f32 v[90:91], v[100:101], v[90:91]
	s_waitcnt lgkmcnt(0)
	v_pk_add_f32 v[4:5], v[4:5], v[2:3]
	v_pk_add_f32 v[6:7], v[6:7], v[0:1]
	ds_read_b128 v[0:3], v150 offset:50176
	v_pk_add_f32 v[72:73], v[80:81], v[72:73]
	v_pk_add_f32 v[82:83], v[90:91], v[82:83]
	v_pk_add_f32 v[64:65], v[72:73], v[64:65]
	v_pk_add_f32 v[74:75], v[82:83], v[74:75]
	s_waitcnt lgkmcnt(0)
	v_pk_add_f32 v[8:9], v[8:9], v[2:3]
	v_pk_add_f32 v[10:11], v[10:11], v[0:1]
	ds_read_b128 v[0:3], v151
	v_pk_add_f32 v[66:67], v[74:75], v[66:67]
	s_add_i32 s7, s7, s92
	s_cmp_lt_i32 s7, 32
	s_waitcnt lgkmcnt(0)
	v_pk_add_f32 v[4:5], v[4:5], v[2:3]
	v_pk_add_f32 v[6:7], v[6:7], v[0:1]
	ds_read_b128 v[0:3], v152
	s_waitcnt lgkmcnt(0)
	v_pk_add_f32 v[8:9], v[8:9], v[2:3]
	v_pk_add_f32 v[10:11], v[10:11], v[0:1]
	ds_read_b128 v[0:3], v153
	s_waitcnt lgkmcnt(0)
	v_pk_add_f32 v[4:5], v[4:5], v[2:3]
	v_pk_add_f32 v[6:7], v[6:7], v[0:1]
	ds_read_b128 v[0:3], v154
	s_waitcnt lgkmcnt(0)
	v_pk_add_f32 v[8:9], v[8:9], v[2:3]
	v_pk_add_f32 v[10:11], v[10:11], v[0:1]
	ds_read_b128 v[0:3], v155
	s_waitcnt lgkmcnt(0)
	v_pk_add_f32 v[4:5], v[4:5], v[2:3]
	v_pk_add_f32 v[6:7], v[6:7], v[0:1]
	ds_read_b128 v[0:3], v156
	s_waitcnt lgkmcnt(0)
	v_pk_add_f32 v[8:9], v[8:9], v[2:3]
	v_pk_add_f32 v[10:11], v[10:11], v[0:1]
	ds_read_b128 v[0:3], v157
	s_waitcnt lgkmcnt(0)
	v_pk_add_f32 v[12:13], v[4:5], v[2:3]
	ds_read_b128 v[2:5], v158
	v_pk_add_f32 v[6:7], v[6:7], v[0:1]
	s_waitcnt lgkmcnt(0)
	s_waitcnt lgkmcnt(0)
	s_barrier
	s_mul_i32 exec_lo, s32, -1
	s_mov_b32 exec_hi, exec_lo
	v_pk_add_f32 v[0:1], v[8:9], v[4:5]
	v_or_b32_e32 v4, s8, v96
	v_ashrrev_i32_e32 v5, 31, v4
	v_lshlrev_b64 v[8:9], 1, v[4:5]
	v_pk_add_f32 v[2:3], v[10:11], v[2:3]
	v_lshl_add_u64 v[10:11], v[138:139], 0, v[8:9]
	v_lshl_add_u64 v[16:17], v[140:141], 0, v[8:9]
	global_load_dwordx2 v[14:15], v[10:11], off offset:2560
	v_mov_b32_e32 v21, v6
	global_load_dwordx2 v[16:17], v[16:17], off
	v_mov_b32_e32 v6, v69
	v_or_b32_e32 v4, 16, v4
	v_lshl_add_u64 v[8:9], v[142:143], 0, v[8:9]
	s_waitcnt vmcnt(0) lgkmcnt(0)
	v_lshlrev_b32_e32 v18, 16, v14
	v_lshlrev_b32_e32 v19, 16, v16
	v_pk_mul_f32 v[18:19], v[20:21], v[18:19]
	s_nop 0
	v_add_f32_e32 v5, v18, v19
	v_and_b32_e32 v19, 0xffff0000, v16
	v_and_b32_e32 v18, 0xffff0000, v14
	v_pk_mul_f32 v[6:7], v[6:7], v[18:19]
	v_mov_b32_e32 v18, v70
	v_add_f32_e32 v14, v6, v7
	v_lshlrev_b32_e32 v7, 16, v17
	v_lshlrev_b32_e32 v6, 16, v15
	v_mov_b32_e32 v19, v12
	v_pk_mul_f32 v[6:7], v[18:19], v[6:7]
	v_mov_b32_e32 v12, v71
	v_add_f32_e32 v16, v6, v7
	v_and_b32_e32 v7, 0xffff0000, v17
	v_and_b32_e32 v6, 0xffff0000, v15
	v_pk_mul_f32 v[6:7], v[12:13], v[6:7]
	v_mov_b32_e32 v12, v64
	v_add_f32_e32 v7, v6, v7
	v_cvt_pk_bf16_f32 v6, v5, v14
	v_ashrrev_i32_e32 v5, 31, v4
	v_cvt_pk_bf16_f32 v7, v16, v7
	v_lshl_add_u64 v[4:5], v[4:5], 1, v[140:141]
	global_store_dwordx2 v[8:9], v[6:7], off
	global_load_dwordx2 v[6:7], v[10:11], off offset:2592
	v_mov_b32_e32 v13, v2
	global_load_dwordx2 v[4:5], v[4:5], off
	v_mov_b32_e32 v2, v65
	s_waitcnt vmcnt(0) lgkmcnt(0)
	v_lshlrev_b32_e32 v10, 16, v6
	v_lshlrev_b32_e32 v11, 16, v4
	v_pk_mul_f32 v[10:11], v[12:13], v[10:11]
	s_nop 0
	v_add_f32_e32 v12, v10, v11
	v_and_b32_e32 v11, 0xffff0000, v4
	v_and_b32_e32 v10, 0xffff0000, v6
	v_pk_mul_f32 v[2:3], v[2:3], v[10:11]
	v_mov_b32_e32 v10, v66
	v_add_f32_e32 v4, v2, v3
	v_lshlrev_b32_e32 v3, 16, v5
	v_lshlrev_b32_e32 v2, 16, v7
	v_mov_b32_e32 v11, v0
	v_pk_mul_f32 v[2:3], v[10:11], v[2:3]
	v_mov_b32_e32 v0, v67
	v_add_f32_e32 v6, v2, v3
	v_and_b32_e32 v3, 0xffff0000, v5
	v_and_b32_e32 v2, 0xffff0000, v7
	v_pk_mul_f32 v[0:1], v[0:1], v[2:3]
	s_nop 0
	v_add_f32_e32 v1, v0, v1
	v_cvt_pk_bf16_f32 v0, v12, v4
	v_cvt_pk_bf16_f32 v1, v6, v1
	global_store_dwordx2 v[8:9], v[0:1], off offset:32
	s_cbranch_scc1 .LBB0_709
; #define PG8_STAGE(bufoff, gbase, voff) do { _Pragma("unroll") for (int _i = 0; _i < 2; ++_i) \
;         __builtin_amdgcn_global_load_lds((const unsigned*)((const char*)(gbase) + (voff)[_i]), (LAS unsigned*)(lds + (bufoff) + ldsw + _i * 8192), 16, 0, 0); } while (0)
; #define PG8_WAIT_V(n) asm volatile("s_waitcnt vmcnt(" #n ")" ::: "memory")
; #define PG8_BAR __builtin_amdgcn_s_barrier()
;     __device__ __forceinline__ bool next(int i, Unit& u) const { u.z = 0; return o.tile(i, u); }
;     __device__ __forceinline__ long a_off(const Unit& u) const { return (long)u.pm * tA; }
;     __device__ __forceinline__ long b_off(const Unit& u) const { return (long)u.pn * tB; }
;     __device__ __forceinline__ bool next(int i, Unit& u) const { u.z = i & 1; return o.tile(i >> 1, u); }
; template <class Epi, class Sched>
; __device__ __forceinline__ void gemm_phase(LAS unsigned char* lds, const Gemm g, const Sched& S, const Epi& E) {
;     ...
;     for (int i = 0; i < 2; ++i) { int R, C; stage_rc(tid * 16 + i * 8192, R, C); const int Rb = Epi::PERM ? ((R & ~31) + perm32(R & 31)) : R;
;         voffA[i] = (unsigned)(R * g.lda + C) * 2u; voffB[i] = (unsigned)(Rb * g.ldb + C) * 2u; }
;     const size_t kstep = (size_t)(BK * 2);
;     const size_t hstepA = (size_t)HALF * g.lda * 2, hstepB = (size_t)HALF * g.ldb * 2;
;     const unsigned ldsw = (unsigned)wid * 1024u;
;     const int aoff = lds_byte(wr * 64 + fr, fq * 8), boff = lds_byte(wc * 32 + fr, fq * 8);
;     ...
;     Unit cur, nxt; int ui = 0;
;     if (!S.next(0, cur)) return;
;     f32x4 acc[2][2][4][2];
; #pragma unroll
;     for (int a = 0; a < 2; ++a)
; #pragma unroll
;         for (int b = 0; b < 2; ++b)
; #pragma unroll
;             for (int m = 0; m < 4; ++m)
; #pragma unroll
;                 for (int n = 0; n < 2; ++n) acc[a][b][m][n] = (f32x4){0.f, 0.f, 0.f, 0.f};
;     bf16x8 At[4][2], B0[2][2], B1[2][2];
;     const char* cA = (const char*)g.A + S.a_off(cur); const char* cB = (const char*)g.Bt + S.b_off(cur);
;     PG8_STAGE(PG8_SB(0, 0), cB, voffB); PG8_STAGE(PG8_SB(0, 1), cB + hstepB, voffB); PG8_STAGE(PG8_SA(0, 0), cA, voffA); PG8_STAGE(PG8_SA(0, 1), cA + hstepA, voffA);
;     if (wr == 1) PG8_BAR;
;     PG8_WAIT_V(2); PG8_BAR;
;     PG8_STAGE(PG8_SB(1, 0), cB + kstep, voffB); PG8_STAGE(PG8_SA(1, 0), cA + kstep, voffA); PG8_STAGE(PG8_SB(1, 1), cB + hstepB + kstep, voffB);
;     PG8_WAIT_V(6); PG8_BAR;
.LBB0_714:
	s_mov_b64 exec, -1
	v_readlane_b32 s0, v247, 10
	v_readlane_b32 s1, v247, 11
	v_mov_b32_e32 v8, v222
	s_andn2_b64 vcc, exec, s[0:1]
	v_cndmask_b32_e64 v0, 0, 1, s[0:1]
	v_cmp_ne_u32_e64 s[2:3], 1, v0
	s_nop 1
	v_writelane_b32 v246, s2, 24
	s_nop 1
	v_writelane_b32 v246, s3, 25
	v_readfirstlane_b32 s2, v8
	s_cbranch_vccnz .LBB0_805
	v_lshlrev_b32_e32 v0, 4, v8
	v_add_u32_e32 v1, 0x2000, v0
	v_ashrrev_i32_e32 v2, 31, v1
	v_lshrrev_b32_e32 v2, 22, v2
	v_add_u32_e32 v2, v1, v2
	v_ashrrev_i32_e32 v9, 10, v2
	v_mul_i32_i24_e32 v2, 0x400, v9
	v_sub_u32_e32 v1, v1, v2
	v_lshrrev_b32_e32 v2, 4, v1
	v_bitop3_b32 v1, v2, v1, 32 bitop3:0x6c
	v_ashrrev_i32_e32 v2, 31, v1
	v_lshrrev_b32_e32 v2, 26, v2
	s_ashr_i32 s3, s2, 6
	v_add_u32_e32 v2, v1, v2
	v_lshlrev_b32_e32 v3, 3, v9
	s_ashr_i32 s8, s2, 8
	s_lshl_b32 s7, s3, 10
	v_readlane_b32 s0, v246, 16
	v_ashrrev_i32_e32 v10, 6, v2
	v_and_b32_e32 v3, -16, v3
	s_add_u32 s22, s0, 0x680000
	v_readlane_b32 s0, v246, 17
	v_add_u32_e32 v3, v10, v3
	s_addc_u32 s23, s0, 0
	v_and_b32_e32 v4, 3, v10
	s_mov_b32 s0, 0x3fffe0
	v_lshrrev_b32_e32 v5, 2, v3
	v_lshlrev_b32_e32 v6, 1, v3
	v_and_b32_e32 v2, 0xc0, v2
	v_and_or_b32 v4, v3, s0, v4
	v_and_b32_e32 v5, 4, v5
	v_and_b32_e32 v6, 24, v6
	v_sub_u32_e32 v1, v1, v2
	v_or3_b32 v4, v4, v5, v6
	v_lshlrev_b32_e32 v5, 5, v9
	v_ashrrev_i16_sdwa v1, v224, sext(v1) dst_sel:DWORD dst_unused:UNUSED_PAD src0_sel:DWORD src1_sel:BYTE_0
	v_and_b32_e32 v5, 32, v5
	v_bfe_i32 v11, v1, 0, 16
	v_add_lshl_u32 v1, v5, v11, 1
	v_lshl_add_u32 v192, v4, 10, v1
	v_lshl_add_u32 v206, v3, 11, v1
	v_bfe_i32 v1, v8, 27, 1
	v_lshrrev_b32_e32 v1, 22, v1
	v_add_u32_e32 v1, v0, v1
	v_and_b32_e32 v1, 0xfffffc00, v1
	v_sub_u32_e32 v0, v0, v1
	v_lshrrev_b32_e32 v1, 4, v0
	v_ashrrev_i32_e32 v2, 31, v8
	v_bitop3_b32 v0, v1, v0, 32 bitop3:0x6c
	v_lshrrev_b32_e32 v2, 26, v2
	v_ashrrev_i32_e32 v1, 31, v0
	v_add_u32_e32 v2, v8, v2
	v_lshrrev_b32_e32 v1, 26, v1
	v_ashrrev_i32_e32 v13, 6, v2
	v_add_u32_e32 v1, v0, v1
	v_lshlrev_b32_e32 v2, 3, v13
	v_ashrrev_i32_e32 v12, 6, v1
	v_and_b32_e32 v2, -16, v2
	v_add_u32_e32 v2, v12, v2
	v_and_b32_e32 v3, 3, v12
	v_lshrrev_b32_e32 v4, 2, v2
	v_lshlrev_b32_e32 v5, 1, v2
	v_and_b32_e32 v1, 0xc0, v1
	v_and_or_b32 v3, v2, s0, v3
	v_and_b32_e32 v4, 4, v4
	v_and_b32_e32 v5, 24, v5
	v_sub_u32_e32 v0, v0, v1
	v_or3_b32 v3, v3, v4, v5
	v_lshlrev_b32_e32 v4, 5, v13
	v_ashrrev_i16_sdwa v0, v224, sext(v0) dst_sel:DWORD dst_unused:UNUSED_PAD src0_sel:DWORD src1_sel:BYTE_0
	v_readlane_b32 s0, v247, 35
	v_and_b32_e32 v4, 32, v4
	v_bfe_i32 v14, v0, 0, 16
	v_readlane_b32 s1, v247, 36
	s_add_u32 s16, s22, s0
	v_add_lshl_u32 v0, v4, v14, 1
	s_addc_u32 s17, s23, s1
	s_add_i32 s25, s7, 0
	v_lshl_add_u32 v208, v3, 10, v0
	s_add_i32 m0, s25, 0x10000
	v_lshl_add_u32 v210, v2, 11, v0
	global_load_lds_dwordx4 v208, s[16:17]
	s_add_i32 m0, s25, 0x12000
	s_add_u32 s0, s16, 0x20000
	global_load_lds_dwordx4 v192, s[16:17]
	s_addc_u32 s1, s17, 0
	s_add_i32 m0, s25, 0x14000
	v_mov_b32_e32 v209, v97
	global_load_lds_dwordx4 v208, s[0:1]
	s_add_i32 m0, s25, 0x16000
	v_mov_b32_e32 v193, v97
	global_load_lds_dwordx4 v192, s[0:1]
	v_readlane_b32 s0, v247, 33
	v_readlane_b32 s1, v247, 34
	s_add_u32 s18, s48, s0
	s_addc_u32 s19, s49, s1
	s_add_i32 s27, s25, 0x2000
	s_mov_b32 m0, s25
	s_add_u32 s0, s18, 0x40000
	global_load_lds_dwordx4 v210, s[18:19]
	s_mov_b32 m0, s27
	s_addc_u32 s1, s19, 0
	s_add_i32 s29, s25, 0x4000
	global_load_lds_dwordx4 v206, s[18:19]
	s_mov_b32 m0, s29
	s_add_i32 s31, s25, 0x6000
	global_load_lds_dwordx4 v210, s[0:1]
	s_mov_b32 m0, s31
	v_mov_b32_e32 v211, v97
	global_load_lds_dwordx4 v206, s[0:1]
	v_mov_b32_e32 v207, v97
	s_cmp_eq_u32 s8, 1
	v_lshl_add_u64 v[6:7], s[16:17], 0, v[208:209]
	v_lshl_add_u64 v[4:5], s[16:17], 0, v[192:193]
	v_lshl_add_u64 v[0:1], s[18:19], 0, v[210:211]
	s_cselect_b64 s[0:1], -1, 0
	s_cmp_lg_u32 s8, 1
	v_lshl_add_u64 v[2:3], s[18:19], 0, v[206:207]
	s_cbranch_scc1 .LBB0_717
	s_barrier
